# MLA q up-projection hand-written on the same scheme (K=256, rope in the row-per-lane epilogue); compiled gemm_mid loop keeps only the conv pointwise tiles
# speedup vs baseline: 1.0163x; 1.0065x over previous
.Lkv_done:
	s_waitcnt vmcnt(0)
	v_mov_b32_e32 v0, v143
	s_and_b64 vcc, exec, s[72:73]
	v_and_b32_e32 v248, 31, v143
	v_bfe_u32 v249, v143, 5, 1
	v_lshrrev_b32_e32 v250, 6, v143
	v_lshl_add_u32 v250, v250, 5, v248
	v_lshlrev_b32_e32 v251, 4, v249
	v_mul_u32_u24_e32 v242, 0x1440, v250
	v_lshl_add_u32 v242, v249, 4, v242
	v_lshlrev_b32_e32 v243, 3, v250
	v_mul_u32_u24_e32 v244, 192, v250
	v_lshl_add_u32 v244, v249, 5, v244
	v_lshrrev_b32_e32 v245, 5, v143
	v_mul_u32_u24_e32 v245, 528, v245
	v_and_b32_e32 v246, 31, v143
	v_lshl_add_u32 v245, v246, 4, v245
	v_lshlrev_b32_e32 v246, 4, v143
	v_add_u32_e32 v164, 0x2000, v246
	v_mul_u32_u24_e32 v247, 528, v248
	v_lshl_add_u32 v247, v249, 4, v247
	s_cmp_lg_u64 s[90:91], 0
	s_movk_i32 s0, 136
	s_cselect_b32 s22, 128, s0
	s_mul_i32 s22, s22, 18
	v_readlane_b32 s0, v253, 0
	s_and_b32 s1, s0, 7
	s_lshl_b32 s1, s1, 5
	s_lshr_b32 s0, s0, 3
	s_add_u32 s0, s0, s1
	s_mul_i32 s4, s0, s22
	s_lshr_b32 s4, s4, 8
	s_add_u32 s0, s0, 1
	s_mul_i32 s5, s0, s22
	s_lshr_b32 s5, s5, 8
	s_mul_i32 s0, s74, 327680
	s_add_u32 s0, s0, 0xb00000
	s_add_u32 s8, s50, s0
	s_addc_u32 s9, s51, 0
	s_add_u32 s30, s50, 0x1076000
	s_addc_u32 s31, s51, 0
	s_mov_b32 s23, 0x3e16c740
	s_mul_hi_u32 s59, s4, 0x38e38e39
	s_lshr_b32 s59, s59, 2
	s_add_u32 s6, s59, 1
	s_mul_i32 s6, s6, 18
	s_min_u32 s6, s6, s5
	s_lshl_b32 s32, s59, 8
	s_lshr_b32 s54, s32, 12
	s_and_b32 s55, s32, 0xfff
	s_sub_u32 s56, s32, 0x8000
	s_lshr_b32 s56, s56, 8
	s_movk_i32 s58, 0x1000
	s_cmp_lt_u32 s32, 0x8000
	s_cselect_b32 s54, s54, s56
	s_cselect_b32 s55, s55, s58
	s_cselect_b32 s19, 1, 0
	s_mul_i32 s54, s54, 26112
	s_add_u32 s18, s54, s55
	s_mul_i32 s54, s32, 5184
	s_add_u32 s54, s54, 0x5cbd000
	s_add_u32 s20, s50, s54
	s_addc_u32 s21, s51, 0
	s_lshl_b32 s54, s32, 3
	s_add_u32 s54, s54, 0x1079000
	s_add_u32 s26, s50, s54
	s_addc_u32 s27, s51, 0
	global_load_dwordx4 v[48:51], v242, s[20:21] offset:0
	global_load_dwordx4 v[52:55], v242, s[20:21] offset:32
	global_load_dwordx4 v[56:59], v242, s[20:21] offset:64
	global_load_dwordx4 v[60:63], v242, s[20:21] offset:96
	global_load_dwordx4 v[64:67], v242, s[20:21] offset:128
	global_load_dwordx4 v[68:71], v242, s[20:21] offset:160
	global_load_dwordx4 v[72:75], v242, s[20:21] offset:192
	global_load_dwordx4 v[76:79], v242, s[20:21] offset:224
	global_load_dwordx4 v[96:99], v242, s[20:21] offset:256
	global_load_dwordx4 v[100:103], v242, s[20:21] offset:288
	global_load_dwordx4 v[104:107], v242, s[20:21] offset:320
	global_load_dwordx4 v[108:111], v242, s[20:21] offset:352
	global_load_dwordx4 v[112:115], v242, s[20:21] offset:384
	global_load_dwordx4 v[116:119], v242, s[20:21] offset:416
	global_load_dwordx4 v[120:123], v242, s[20:21] offset:448
	global_load_dwordx4 v[124:127], v242, s[20:21] offset:480
	global_load_dword v154, v243, s[26:27]
	v_add_u32_e32 v162, s55, v250
	v_and_b32_e32 v162, 0xfff, v162
	v_lshrrev_b32_e32 v163, 6, v162
	v_lshl_add_u32 v163, v163, 5, v251
	global_load_dwordx4 v[130:133], v163, s[30:31]
	global_load_dwordx4 v[134:137], v163, s[30:31] offset:2048
	v_and_b32_e32 v162, 63, v162
	v_lshl_add_u32 v162, v162, 5, v251
	global_load_dwordx4 v[138:141], v162, s[30:31]
	global_load_dwordx4 v[158:161], v162, s[30:31] offset:2048
	s_mov_b32 s25, s4
	s_add_u32 s0, s5, -1
	s_min_u32 s0, s25, s0
	s_mul_hi_u32 s1, s0, 0x38e38e39
	s_lshr_b32 s1, s1, 2
	s_mul_i32 s1, s1, 18
	s_sub_u32 s0, s0, s1
	s_lshl_b32 s0, s0, 14
	s_add_u32 s10, s8, s0
	s_addc_u32 s11, s9, 0
	global_load_dwordx4 v[220:223], v246, s[10:11]
	global_load_dwordx4 v[224:227], v164, s[10:11]
	s_add_u32 s25, s25, 1
	s_add_u32 s0, s5, -1
	s_min_u32 s0, s25, s0
	s_mul_hi_u32 s1, s0, 0x38e38e39
	s_lshr_b32 s1, s1, 2
	s_mul_i32 s1, s1, 18
	s_sub_u32 s0, s0, s1
	s_lshl_b32 s0, s0, 14
	s_add_u32 s10, s8, s0
	s_addc_u32 s11, s9, 0
	global_load_dwordx4 v[228:231], v246, s[10:11]
	global_load_dwordx4 v[238:241], v164, s[10:11]
	s_add_u32 s25, s25, 1
	s_waitcnt vmcnt(0)
	ds_write_b128 v245, v[220:223]
	ds_write_b128 v245, v[224:227] offset:8448
	s_add_u32 s0, s5, -1
	s_min_u32 s0, s25, s0
	s_mul_hi_u32 s1, s0, 0x38e38e39
	s_lshr_b32 s1, s1, 2
	s_mul_i32 s1, s1, 18
	s_sub_u32 s0, s0, s1
	s_lshl_b32 s0, s0, 14
	s_add_u32 s10, s8, s0
	s_addc_u32 s11, s9, 0
	global_load_dwordx4 v[220:223], v246, s[10:11]
	global_load_dwordx4 v[224:227], v164, s[10:11]
	s_add_u32 s25, s25, 1
	global_load_dword v156, v243, s[26:27]
	global_load_dword v157, v243, s[26:27]
	s_waitcnt lgkmcnt(0)
	s_barrier
	s_mov_b32 s16, 0
.Lq_loop:
	s_waitcnt vmcnt(6)
	ds_write_b128 v245, v[228:231] offset:16896
	ds_write_b128 v245, v[238:241] offset:25344
	s_add_u32 s0, s5, -1
	s_min_u32 s0, s25, s0
	s_mul_hi_u32 s1, s0, 0x38e38e39
	s_lshr_b32 s1, s1, 2
	s_mul_i32 s1, s1, 18
	s_sub_u32 s0, s0, s1
	s_lshl_b32 s0, s0, 14
	s_add_u32 s10, s8, s0
	s_addc_u32 s11, s9, 0
	global_load_dwordx4 v[228:231], v246, s[10:11]
	global_load_dwordx4 v[238:241], v164, s[10:11]
	s_add_u32 s25, s25, 1
	s_mul_hi_u32 s1, s4, 0x38e38e39
	s_lshr_b32 s1, s1, 2
	s_mul_i32 s1, s1, 18
	s_sub_u32 s0, s4, s1
	s_mul_hi_u32 s1, s0, 0xaaaaaaab
	s_lshr_b32 s1, s1, 1
	s_mul_i32 s32, s1, 3
	s_sub_u32 s32, s0, s32
	s_mul_i32 s1, s1, 4352
	s_add_u32 s1, s1, s18
	s_mul_i32 s1, s1, 192
	s_lshl_b32 s54, s32, 6
	s_add_u32 s1, s1, s54
	s_add_u32 s1, s1, 0x108dd000
	s_add_u32 s14, s50, s1
	s_addc_u32 s15, s51, 0
	s_cmp_eq_u32 s32, 2
	s_cselect_b32 s17, s19, 0
	s_add_u32 s17, s17, 1
	ds_read_b128 v[188:191], v247 offset:0
	ds_read_b128 v[192:195], v247 offset:32
	ds_read_b128 v[196:199], v247 offset:64
	ds_read_b128 v[200:203], v247 offset:96
	ds_read_b128 v[204:207], v247 offset:128
	ds_read_b128 v[208:211], v247 offset:160
	ds_read_b128 v[212:215], v247 offset:192
	ds_read_b128 v[216:219], v247 offset:224
	s_waitcnt lgkmcnt(7)
	v_mfma_f32_32x32x16_bf16 v[0:15], v[188:191], v[48:51], 0
	ds_read_b128 v[188:191], v247 offset:256
	s_waitcnt lgkmcnt(7)
	v_mfma_f32_32x32x16_bf16 v[0:15], v[192:195], v[52:55], v[0:15]
	ds_read_b128 v[192:195], v247 offset:288
	s_waitcnt lgkmcnt(7)
	v_mfma_f32_32x32x16_bf16 v[0:15], v[196:199], v[56:59], v[0:15]
	ds_read_b128 v[196:199], v247 offset:320
	s_waitcnt lgkmcnt(7)
	v_mfma_f32_32x32x16_bf16 v[0:15], v[200:203], v[60:63], v[0:15]
	ds_read_b128 v[200:203], v247 offset:352
	s_waitcnt lgkmcnt(7)
	v_mfma_f32_32x32x16_bf16 v[0:15], v[204:207], v[64:67], v[0:15]
	ds_read_b128 v[204:207], v247 offset:384
	s_waitcnt lgkmcnt(7)
	v_mfma_f32_32x32x16_bf16 v[0:15], v[208:211], v[68:71], v[0:15]
	ds_read_b128 v[208:211], v247 offset:416
	s_waitcnt lgkmcnt(7)
	v_mfma_f32_32x32x16_bf16 v[0:15], v[212:215], v[72:75], v[0:15]
	ds_read_b128 v[212:215], v247 offset:448
	s_waitcnt lgkmcnt(7)
	v_mfma_f32_32x32x16_bf16 v[0:15], v[216:219], v[76:79], v[0:15]
	ds_read_b128 v[216:219], v247 offset:480
	s_waitcnt lgkmcnt(7)
	v_mfma_f32_32x32x16_bf16 v[0:15], v[188:191], v[96:99], v[0:15]
	s_waitcnt lgkmcnt(6)
	v_mfma_f32_32x32x16_bf16 v[0:15], v[192:195], v[100:103], v[0:15]
	s_waitcnt lgkmcnt(5)
	v_mfma_f32_32x32x16_bf16 v[0:15], v[196:199], v[104:107], v[0:15]
	s_waitcnt lgkmcnt(4)
	v_mfma_f32_32x32x16_bf16 v[0:15], v[200:203], v[108:111], v[0:15]
	s_waitcnt lgkmcnt(3)
	v_mfma_f32_32x32x16_bf16 v[0:15], v[204:207], v[112:115], v[0:15]
	s_waitcnt lgkmcnt(2)
	v_mfma_f32_32x32x16_bf16 v[0:15], v[208:211], v[116:119], v[0:15]
	s_waitcnt lgkmcnt(1)
	v_mfma_f32_32x32x16_bf16 v[0:15], v[212:215], v[120:123], v[0:15]
	s_waitcnt lgkmcnt(0)
	v_mfma_f32_32x32x16_bf16 v[0:15], v[216:219], v[124:127], v[0:15]
	s_cmp_eq_u32 s16, 0
	s_cbranch_scc0 .Lq_ep0
	global_load_dword v156, v243, s[26:27]
	global_load_dword v157, v243, s[26:27]
	s_branch .Lq_ex0
.Lq_ep0:
	v_mul_f32_e32 v16, v16, v155
	v_mul_f32_e32 v17, v17, v155
	v_mul_f32_e32 v18, v18, v155
	v_mul_f32_e32 v19, v19, v155
	v_mul_f32_e32 v20, v20, v155
	v_mul_f32_e32 v21, v21, v155
	v_mul_f32_e32 v22, v22, v155
	v_mul_f32_e32 v23, v23, v155
	v_mul_f32_e32 v24, v24, v155
	v_mul_f32_e32 v25, v25, v155
	v_mul_f32_e32 v26, v26, v155
	v_mul_f32_e32 v27, v27, v155
	v_mul_f32_e32 v28, v28, v155
	v_mul_f32_e32 v29, v29, v155
	v_mul_f32_e32 v30, v30, v155
	v_mul_f32_e32 v31, v31, v155
	s_cmp_eq_u32 s16, 2
	s_cbranch_scc0 .Lq_nr0
	v_mul_f32_e32 v162, v20, v134
	v_mul_f32_e32 v163, v16, v134
	v_fma_f32 v16, v16, v130, -v162
	v_fma_f32 v20, v20, v130, v163
	v_mul_f32_e32 v162, v21, v135
	v_mul_f32_e32 v163, v17, v135
	v_fma_f32 v17, v17, v131, -v162
	v_fma_f32 v21, v21, v131, v163
	v_mul_f32_e32 v162, v22, v136
	v_mul_f32_e32 v163, v18, v136
	v_fma_f32 v18, v18, v132, -v162
	v_fma_f32 v22, v22, v132, v163
	v_mul_f32_e32 v162, v23, v137
	v_mul_f32_e32 v163, v19, v137
	v_fma_f32 v19, v19, v133, -v162
	v_fma_f32 v23, v23, v133, v163
	v_mul_f32_e32 v162, v28, v158
	v_mul_f32_e32 v163, v24, v158
	v_fma_f32 v24, v24, v138, -v162
	v_fma_f32 v28, v28, v138, v163
	v_mul_f32_e32 v162, v29, v159
	v_mul_f32_e32 v163, v25, v159
	v_fma_f32 v25, v25, v139, -v162
	v_fma_f32 v29, v29, v139, v163
	v_mul_f32_e32 v162, v30, v160
	v_mul_f32_e32 v163, v26, v160
	v_fma_f32 v26, v26, v140, -v162
	v_fma_f32 v30, v30, v140, v163
	v_mul_f32_e32 v162, v31, v161
	v_mul_f32_e32 v163, v27, v161
	v_fma_f32 v27, v27, v141, -v162
	v_fma_f32 v31, v31, v141, v163
.Lq_nr0:
	v_mul_f32_e32 v16, s23, v16
	v_mul_f32_e32 v17, s23, v17
	v_mul_f32_e32 v18, s23, v18
	v_mul_f32_e32 v19, s23, v19
	v_mul_f32_e32 v20, s23, v20
	v_mul_f32_e32 v21, s23, v21
	v_mul_f32_e32 v22, s23, v22
	v_mul_f32_e32 v23, s23, v23
	v_mul_f32_e32 v24, s23, v24
	v_mul_f32_e32 v25, s23, v25
	v_mul_f32_e32 v26, s23, v26
	v_mul_f32_e32 v27, s23, v27
	v_mul_f32_e32 v28, s23, v28
	v_mul_f32_e32 v29, s23, v29
	v_mul_f32_e32 v30, s23, v30
	v_mul_f32_e32 v31, s23, v31
	v_cvt_pk_bf16_f32 v144, v16, v17
	v_cvt_pk_bf16_f32 v145, v18, v19
	v_cvt_pk_bf16_f32 v148, v20, v21
	v_cvt_pk_bf16_f32 v149, v22, v23
	v_cvt_pk_bf16_f32 v146, v24, v25
	v_cvt_pk_bf16_f32 v147, v26, v27
	v_cvt_pk_bf16_f32 v150, v28, v29
	v_cvt_pk_bf16_f32 v151, v30, v31
	s_nop 1
	v_permlane32_swap_b32_e32 v144, v146
	v_permlane32_swap_b32_e32 v145, v147
	v_permlane32_swap_b32_e32 v148, v150
	v_permlane32_swap_b32_e32 v149, v151
	global_store_dwordx4 v244, v[144:147], s[12:13]
	global_store_dwordx4 v244, v[148:151], s[12:13] offset:16
.Lq_ex0:
	v_mov_b32_e32 v155, v154
	s_mov_b64 s[12:13], s[14:15]
	s_mov_b32 s16, s17
	s_add_u32 s4, s4, 1
	s_waitcnt lgkmcnt(0)
	s_barrier
	s_cmp_ge_u32 s4, s5
	s_cbranch_scc1 .Lq_drain0
	s_cmp_lg_u32 s4, s6
	s_cbranch_scc1 .Lq_ns0
	s_nop 7
	s_nop 7
	v_mul_f32_e32 v0, v0, v155
	v_mul_f32_e32 v1, v1, v155
	v_mul_f32_e32 v2, v2, v155
	v_mul_f32_e32 v3, v3, v155
	v_mul_f32_e32 v4, v4, v155
	v_mul_f32_e32 v5, v5, v155
	v_mul_f32_e32 v6, v6, v155
	v_mul_f32_e32 v7, v7, v155
	v_mul_f32_e32 v8, v8, v155
	v_mul_f32_e32 v9, v9, v155
	v_mul_f32_e32 v10, v10, v155
	v_mul_f32_e32 v11, v11, v155
	v_mul_f32_e32 v12, v12, v155
	v_mul_f32_e32 v13, v13, v155
	v_mul_f32_e32 v14, v14, v155
	v_mul_f32_e32 v15, v15, v155
	s_cmp_eq_u32 s16, 2
	s_cbranch_scc0 .Lq_nrs0
	v_mul_f32_e32 v162, v4, v134
	v_mul_f32_e32 v163, v0, v134
	v_fma_f32 v0, v0, v130, -v162
	v_fma_f32 v4, v4, v130, v163
	v_mul_f32_e32 v162, v5, v135
	v_mul_f32_e32 v163, v1, v135
	v_fma_f32 v1, v1, v131, -v162
	v_fma_f32 v5, v5, v131, v163
	v_mul_f32_e32 v162, v6, v136
	v_mul_f32_e32 v163, v2, v136
	v_fma_f32 v2, v2, v132, -v162
	v_fma_f32 v6, v6, v132, v163
	v_mul_f32_e32 v162, v7, v137
	v_mul_f32_e32 v163, v3, v137
	v_fma_f32 v3, v3, v133, -v162
	v_fma_f32 v7, v7, v133, v163
	v_mul_f32_e32 v162, v12, v158
	v_mul_f32_e32 v163, v8, v158
	v_fma_f32 v8, v8, v138, -v162
	v_fma_f32 v12, v12, v138, v163
	v_mul_f32_e32 v162, v13, v159
	v_mul_f32_e32 v163, v9, v159
	v_fma_f32 v9, v9, v139, -v162
	v_fma_f32 v13, v13, v139, v163
	v_mul_f32_e32 v162, v14, v160
	v_mul_f32_e32 v163, v10, v160
	v_fma_f32 v10, v10, v140, -v162
	v_fma_f32 v14, v14, v140, v163
	v_mul_f32_e32 v162, v15, v161
	v_mul_f32_e32 v163, v11, v161
	v_fma_f32 v11, v11, v141, -v162
	v_fma_f32 v15, v15, v141, v163
.Lq_nrs0:
	v_mul_f32_e32 v0, s23, v0
	v_mul_f32_e32 v1, s23, v1
	v_mul_f32_e32 v2, s23, v2
	v_mul_f32_e32 v3, s23, v3
	v_mul_f32_e32 v4, s23, v4
	v_mul_f32_e32 v5, s23, v5
	v_mul_f32_e32 v6, s23, v6
	v_mul_f32_e32 v7, s23, v7
	v_mul_f32_e32 v8, s23, v8
	v_mul_f32_e32 v9, s23, v9
	v_mul_f32_e32 v10, s23, v10
	v_mul_f32_e32 v11, s23, v11
	v_mul_f32_e32 v12, s23, v12
	v_mul_f32_e32 v13, s23, v13
	v_mul_f32_e32 v14, s23, v14
	v_mul_f32_e32 v15, s23, v15
	v_cvt_pk_bf16_f32 v144, v0, v1
	v_cvt_pk_bf16_f32 v145, v2, v3
	v_cvt_pk_bf16_f32 v148, v4, v5
	v_cvt_pk_bf16_f32 v149, v6, v7
	v_cvt_pk_bf16_f32 v146, v8, v9
	v_cvt_pk_bf16_f32 v147, v10, v11
	v_cvt_pk_bf16_f32 v150, v12, v13
	v_cvt_pk_bf16_f32 v151, v14, v15
	s_nop 1
	v_permlane32_swap_b32_e32 v144, v146
	v_permlane32_swap_b32_e32 v145, v147
	v_permlane32_swap_b32_e32 v148, v150
	v_permlane32_swap_b32_e32 v149, v151
	global_store_dwordx4 v244, v[144:147], s[12:13]
	global_store_dwordx4 v244, v[148:151], s[12:13] offset:16
	s_mov_b32 s16, 0
	s_mul_hi_u32 s59, s4, 0x38e38e39
	s_lshr_b32 s59, s59, 2
	s_mov_b32 s6, s5
	s_lshl_b32 s32, s59, 8
	s_lshr_b32 s54, s32, 12
	s_and_b32 s55, s32, 0xfff
	s_sub_u32 s56, s32, 0x8000
	s_lshr_b32 s56, s56, 8
	s_movk_i32 s58, 0x1000
	s_cmp_lt_u32 s32, 0x8000
	s_cselect_b32 s54, s54, s56
	s_cselect_b32 s55, s55, s58
	s_cselect_b32 s19, 1, 0
	s_mul_i32 s54, s54, 26112
	s_add_u32 s18, s54, s55
	s_mul_i32 s54, s32, 5184
	s_add_u32 s54, s54, 0x5cbd000
	s_add_u32 s20, s50, s54
	s_addc_u32 s21, s51, 0
	s_lshl_b32 s54, s32, 3
	s_add_u32 s54, s54, 0x1079000
	s_add_u32 s26, s50, s54
	s_addc_u32 s27, s51, 0
	global_load_dwordx4 v[48:51], v242, s[20:21] offset:0
	global_load_dwordx4 v[52:55], v242, s[20:21] offset:32
	global_load_dwordx4 v[56:59], v242, s[20:21] offset:64
	global_load_dwordx4 v[60:63], v242, s[20:21] offset:96
	global_load_dwordx4 v[64:67], v242, s[20:21] offset:128
	global_load_dwordx4 v[68:71], v242, s[20:21] offset:160
	global_load_dwordx4 v[72:75], v242, s[20:21] offset:192
	global_load_dwordx4 v[76:79], v242, s[20:21] offset:224
	global_load_dwordx4 v[96:99], v242, s[20:21] offset:256
	global_load_dwordx4 v[100:103], v242, s[20:21] offset:288
	global_load_dwordx4 v[104:107], v242, s[20:21] offset:320
	global_load_dwordx4 v[108:111], v242, s[20:21] offset:352
	global_load_dwordx4 v[112:115], v242, s[20:21] offset:384
	global_load_dwordx4 v[116:119], v242, s[20:21] offset:416
	global_load_dwordx4 v[120:123], v242, s[20:21] offset:448
	global_load_dwordx4 v[124:127], v242, s[20:21] offset:480
	global_load_dword v154, v243, s[26:27]
	v_add_u32_e32 v162, s55, v250
	v_and_b32_e32 v162, 0xfff, v162
	v_lshrrev_b32_e32 v163, 6, v162
	v_lshl_add_u32 v163, v163, 5, v251
	global_load_dwordx4 v[130:133], v163, s[30:31]
	global_load_dwordx4 v[134:137], v163, s[30:31] offset:2048
	v_and_b32_e32 v162, 63, v162
	v_lshl_add_u32 v162, v162, 5, v251
	global_load_dwordx4 v[138:141], v162, s[30:31]
	global_load_dwordx4 v[158:161], v162, s[30:31] offset:2048
	s_waitcnt vmcnt(0)
.Lq_ns0:
	s_waitcnt vmcnt(6)
	ds_write_b128 v245, v[220:223] offset:0
	ds_write_b128 v245, v[224:227] offset:8448
	s_add_u32 s0, s5, -1
	s_min_u32 s0, s25, s0
	s_mul_hi_u32 s1, s0, 0x38e38e39
	s_lshr_b32 s1, s1, 2
	s_mul_i32 s1, s1, 18
	s_sub_u32 s0, s0, s1
	s_lshl_b32 s0, s0, 14
	s_add_u32 s10, s8, s0
	s_addc_u32 s11, s9, 0
	global_load_dwordx4 v[220:223], v246, s[10:11]
	global_load_dwordx4 v[224:227], v164, s[10:11]
	s_add_u32 s25, s25, 1
	s_mul_hi_u32 s1, s4, 0x38e38e39
	s_lshr_b32 s1, s1, 2
	s_mul_i32 s1, s1, 18
	s_sub_u32 s0, s4, s1
	s_mul_hi_u32 s1, s0, 0xaaaaaaab
	s_lshr_b32 s1, s1, 1
	s_mul_i32 s32, s1, 3
	s_sub_u32 s32, s0, s32
	s_mul_i32 s1, s1, 4352
	s_add_u32 s1, s1, s18
	s_mul_i32 s1, s1, 192
	s_lshl_b32 s54, s32, 6
	s_add_u32 s1, s1, s54
	s_add_u32 s1, s1, 0x108dd000
	s_add_u32 s14, s50, s1
	s_addc_u32 s15, s51, 0
	s_cmp_eq_u32 s32, 2
	s_cselect_b32 s17, s19, 0
	s_add_u32 s17, s17, 1
	ds_read_b128 v[188:191], v247 offset:16896
	ds_read_b128 v[192:195], v247 offset:16928
	ds_read_b128 v[196:199], v247 offset:16960
	ds_read_b128 v[200:203], v247 offset:16992
	ds_read_b128 v[204:207], v247 offset:17024
	ds_read_b128 v[208:211], v247 offset:17056
	ds_read_b128 v[212:215], v247 offset:17088
	ds_read_b128 v[216:219], v247 offset:17120
	s_waitcnt lgkmcnt(7)
	v_mfma_f32_32x32x16_bf16 v[16:31], v[188:191], v[48:51], 0
	ds_read_b128 v[188:191], v247 offset:17152
	s_waitcnt lgkmcnt(7)
	v_mfma_f32_32x32x16_bf16 v[16:31], v[192:195], v[52:55], v[16:31]
	ds_read_b128 v[192:195], v247 offset:17184
	s_waitcnt lgkmcnt(7)
	v_mfma_f32_32x32x16_bf16 v[16:31], v[196:199], v[56:59], v[16:31]
	ds_read_b128 v[196:199], v247 offset:17216
	s_waitcnt lgkmcnt(7)
	v_mfma_f32_32x32x16_bf16 v[16:31], v[200:203], v[60:63], v[16:31]
	ds_read_b128 v[200:203], v247 offset:17248
	s_waitcnt lgkmcnt(7)
	v_mfma_f32_32x32x16_bf16 v[16:31], v[204:207], v[64:67], v[16:31]
	ds_read_b128 v[204:207], v247 offset:17280
	s_waitcnt lgkmcnt(7)
	v_mfma_f32_32x32x16_bf16 v[16:31], v[208:211], v[68:71], v[16:31]
	ds_read_b128 v[208:211], v247 offset:17312
	s_waitcnt lgkmcnt(7)
	v_mfma_f32_32x32x16_bf16 v[16:31], v[212:215], v[72:75], v[16:31]
	ds_read_b128 v[212:215], v247 offset:17344
	s_waitcnt lgkmcnt(7)
	v_mfma_f32_32x32x16_bf16 v[16:31], v[216:219], v[76:79], v[16:31]
	ds_read_b128 v[216:219], v247 offset:17376
	s_waitcnt lgkmcnt(7)
	v_mfma_f32_32x32x16_bf16 v[16:31], v[188:191], v[96:99], v[16:31]
	s_waitcnt lgkmcnt(6)
	v_mfma_f32_32x32x16_bf16 v[16:31], v[192:195], v[100:103], v[16:31]
	s_waitcnt lgkmcnt(5)
	v_mfma_f32_32x32x16_bf16 v[16:31], v[196:199], v[104:107], v[16:31]
	s_waitcnt lgkmcnt(4)
	v_mfma_f32_32x32x16_bf16 v[16:31], v[200:203], v[108:111], v[16:31]
	s_waitcnt lgkmcnt(3)
	v_mfma_f32_32x32x16_bf16 v[16:31], v[204:207], v[112:115], v[16:31]
	s_waitcnt lgkmcnt(2)
	v_mfma_f32_32x32x16_bf16 v[16:31], v[208:211], v[116:119], v[16:31]
	s_waitcnt lgkmcnt(1)
	v_mfma_f32_32x32x16_bf16 v[16:31], v[212:215], v[120:123], v[16:31]
	s_waitcnt lgkmcnt(0)
	v_mfma_f32_32x32x16_bf16 v[16:31], v[216:219], v[124:127], v[16:31]
	s_cmp_eq_u32 s16, 0
	s_cbranch_scc0 .Lq_ep1
	global_load_dword v156, v243, s[26:27]
	global_load_dword v157, v243, s[26:27]
	s_branch .Lq_ex1
.Lq_ep1:
	v_mul_f32_e32 v0, v0, v155
	v_mul_f32_e32 v1, v1, v155
	v_mul_f32_e32 v2, v2, v155
	v_mul_f32_e32 v3, v3, v155
	v_mul_f32_e32 v4, v4, v155
	v_mul_f32_e32 v5, v5, v155
	v_mul_f32_e32 v6, v6, v155
	v_mul_f32_e32 v7, v7, v155
	v_mul_f32_e32 v8, v8, v155
	v_mul_f32_e32 v9, v9, v155
	v_mul_f32_e32 v10, v10, v155
	v_mul_f32_e32 v11, v11, v155
	v_mul_f32_e32 v12, v12, v155
	v_mul_f32_e32 v13, v13, v155
	v_mul_f32_e32 v14, v14, v155
	v_mul_f32_e32 v15, v15, v155
	s_cmp_eq_u32 s16, 2
	s_cbranch_scc0 .Lq_nr1
	v_mul_f32_e32 v162, v4, v134
	v_mul_f32_e32 v163, v0, v134
	v_fma_f32 v0, v0, v130, -v162
	v_fma_f32 v4, v4, v130, v163
	v_mul_f32_e32 v162, v5, v135
	v_mul_f32_e32 v163, v1, v135
	v_fma_f32 v1, v1, v131, -v162
	v_fma_f32 v5, v5, v131, v163
	v_mul_f32_e32 v162, v6, v136
	v_mul_f32_e32 v163, v2, v136
	v_fma_f32 v2, v2, v132, -v162
	v_fma_f32 v6, v6, v132, v163
	v_mul_f32_e32 v162, v7, v137
	v_mul_f32_e32 v163, v3, v137
	v_fma_f32 v3, v3, v133, -v162
	v_fma_f32 v7, v7, v133, v163
	v_mul_f32_e32 v162, v12, v158
	v_mul_f32_e32 v163, v8, v158
	v_fma_f32 v8, v8, v138, -v162
	v_fma_f32 v12, v12, v138, v163
	v_mul_f32_e32 v162, v13, v159
	v_mul_f32_e32 v163, v9, v159
	v_fma_f32 v9, v9, v139, -v162
	v_fma_f32 v13, v13, v139, v163
	v_mul_f32_e32 v162, v14, v160
	v_mul_f32_e32 v163, v10, v160
	v_fma_f32 v10, v10, v140, -v162
	v_fma_f32 v14, v14, v140, v163
	v_mul_f32_e32 v162, v15, v161
	v_mul_f32_e32 v163, v11, v161
	v_fma_f32 v11, v11, v141, -v162
	v_fma_f32 v15, v15, v141, v163
.Lq_nr1:
	v_mul_f32_e32 v0, s23, v0
	v_mul_f32_e32 v1, s23, v1
	v_mul_f32_e32 v2, s23, v2
	v_mul_f32_e32 v3, s23, v3
	v_mul_f32_e32 v4, s23, v4
	v_mul_f32_e32 v5, s23, v5
	v_mul_f32_e32 v6, s23, v6
	v_mul_f32_e32 v7, s23, v7
	v_mul_f32_e32 v8, s23, v8
	v_mul_f32_e32 v9, s23, v9
	v_mul_f32_e32 v10, s23, v10
	v_mul_f32_e32 v11, s23, v11
	v_mul_f32_e32 v12, s23, v12
	v_mul_f32_e32 v13, s23, v13
	v_mul_f32_e32 v14, s23, v14
	v_mul_f32_e32 v15, s23, v15
	v_cvt_pk_bf16_f32 v144, v0, v1
	v_cvt_pk_bf16_f32 v145, v2, v3
	v_cvt_pk_bf16_f32 v148, v4, v5
	v_cvt_pk_bf16_f32 v149, v6, v7
	v_cvt_pk_bf16_f32 v146, v8, v9
	v_cvt_pk_bf16_f32 v147, v10, v11
	v_cvt_pk_bf16_f32 v150, v12, v13
	v_cvt_pk_bf16_f32 v151, v14, v15
	s_nop 1
	v_permlane32_swap_b32_e32 v144, v146
	v_permlane32_swap_b32_e32 v145, v147
	v_permlane32_swap_b32_e32 v148, v150
	v_permlane32_swap_b32_e32 v149, v151
	global_store_dwordx4 v244, v[144:147], s[12:13]
	global_store_dwordx4 v244, v[148:151], s[12:13] offset:16
.Lq_ex1:
	v_mov_b32_e32 v155, v154
	s_mov_b64 s[12:13], s[14:15]
	s_mov_b32 s16, s17
	s_add_u32 s4, s4, 1
	s_waitcnt lgkmcnt(0)
	s_barrier
	s_cmp_ge_u32 s4, s5
	s_cbranch_scc1 .Lq_drain1
	s_cmp_lg_u32 s4, s6
	s_cbranch_scc1 .Lq_ns1
	s_nop 7
	s_nop 7
	v_mul_f32_e32 v16, v16, v155
	v_mul_f32_e32 v17, v17, v155
	v_mul_f32_e32 v18, v18, v155
	v_mul_f32_e32 v19, v19, v155
	v_mul_f32_e32 v20, v20, v155
	v_mul_f32_e32 v21, v21, v155
	v_mul_f32_e32 v22, v22, v155
	v_mul_f32_e32 v23, v23, v155
	v_mul_f32_e32 v24, v24, v155
	v_mul_f32_e32 v25, v25, v155
	v_mul_f32_e32 v26, v26, v155
	v_mul_f32_e32 v27, v27, v155
	v_mul_f32_e32 v28, v28, v155
	v_mul_f32_e32 v29, v29, v155
	v_mul_f32_e32 v30, v30, v155
	v_mul_f32_e32 v31, v31, v155
	s_cmp_eq_u32 s16, 2
	s_cbranch_scc0 .Lq_nrs1
	v_mul_f32_e32 v162, v20, v134
	v_mul_f32_e32 v163, v16, v134
	v_fma_f32 v16, v16, v130, -v162
	v_fma_f32 v20, v20, v130, v163
	v_mul_f32_e32 v162, v21, v135
	v_mul_f32_e32 v163, v17, v135
	v_fma_f32 v17, v17, v131, -v162
	v_fma_f32 v21, v21, v131, v163
	v_mul_f32_e32 v162, v22, v136
	v_mul_f32_e32 v163, v18, v136
	v_fma_f32 v18, v18, v132, -v162
	v_fma_f32 v22, v22, v132, v163
	v_mul_f32_e32 v162, v23, v137
	v_mul_f32_e32 v163, v19, v137
	v_fma_f32 v19, v19, v133, -v162
	v_fma_f32 v23, v23, v133, v163
	v_mul_f32_e32 v162, v28, v158
	v_mul_f32_e32 v163, v24, v158
	v_fma_f32 v24, v24, v138, -v162
	v_fma_f32 v28, v28, v138, v163
	v_mul_f32_e32 v162, v29, v159
	v_mul_f32_e32 v163, v25, v159
	v_fma_f32 v25, v25, v139, -v162
	v_fma_f32 v29, v29, v139, v163
	v_mul_f32_e32 v162, v30, v160
	v_mul_f32_e32 v163, v26, v160
	v_fma_f32 v26, v26, v140, -v162
	v_fma_f32 v30, v30, v140, v163
	v_mul_f32_e32 v162, v31, v161
	v_mul_f32_e32 v163, v27, v161
	v_fma_f32 v27, v27, v141, -v162
	v_fma_f32 v31, v31, v141, v163
.Lq_nrs1:
	v_mul_f32_e32 v16, s23, v16
	v_mul_f32_e32 v17, s23, v17
	v_mul_f32_e32 v18, s23, v18
	v_mul_f32_e32 v19, s23, v19
	v_mul_f32_e32 v20, s23, v20
	v_mul_f32_e32 v21, s23, v21
	v_mul_f32_e32 v22, s23, v22
	v_mul_f32_e32 v23, s23, v23
	v_mul_f32_e32 v24, s23, v24
	v_mul_f32_e32 v25, s23, v25
	v_mul_f32_e32 v26, s23, v26
	v_mul_f32_e32 v27, s23, v27
	v_mul_f32_e32 v28, s23, v28
	v_mul_f32_e32 v29, s23, v29
	v_mul_f32_e32 v30, s23, v30
	v_mul_f32_e32 v31, s23, v31
	v_cvt_pk_bf16_f32 v144, v16, v17
	v_cvt_pk_bf16_f32 v145, v18, v19
	v_cvt_pk_bf16_f32 v148, v20, v21
	v_cvt_pk_bf16_f32 v149, v22, v23
	v_cvt_pk_bf16_f32 v146, v24, v25
	v_cvt_pk_bf16_f32 v147, v26, v27
	v_cvt_pk_bf16_f32 v150, v28, v29
	v_cvt_pk_bf16_f32 v151, v30, v31
	s_nop 1
	v_permlane32_swap_b32_e32 v144, v146
	v_permlane32_swap_b32_e32 v145, v147
	v_permlane32_swap_b32_e32 v148, v150
	v_permlane32_swap_b32_e32 v149, v151
	global_store_dwordx4 v244, v[144:147], s[12:13]
	global_store_dwordx4 v244, v[148:151], s[12:13] offset:16
	s_mov_b32 s16, 0
	s_mul_hi_u32 s59, s4, 0x38e38e39
	s_lshr_b32 s59, s59, 2
	s_mov_b32 s6, s5
	s_lshl_b32 s32, s59, 8
	s_lshr_b32 s54, s32, 12
	s_and_b32 s55, s32, 0xfff
	s_sub_u32 s56, s32, 0x8000
	s_lshr_b32 s56, s56, 8
	s_movk_i32 s58, 0x1000
	s_cmp_lt_u32 s32, 0x8000
	s_cselect_b32 s54, s54, s56
	s_cselect_b32 s55, s55, s58
	s_cselect_b32 s19, 1, 0
	s_mul_i32 s54, s54, 26112
	s_add_u32 s18, s54, s55
	s_mul_i32 s54, s32, 5184
	s_add_u32 s54, s54, 0x5cbd000
	s_add_u32 s20, s50, s54
	s_addc_u32 s21, s51, 0
	s_lshl_b32 s54, s32, 3
	s_add_u32 s54, s54, 0x1079000
	s_add_u32 s26, s50, s54
	s_addc_u32 s27, s51, 0
	global_load_dwordx4 v[48:51], v242, s[20:21] offset:0
	global_load_dwordx4 v[52:55], v242, s[20:21] offset:32
	global_load_dwordx4 v[56:59], v242, s[20:21] offset:64
	global_load_dwordx4 v[60:63], v242, s[20:21] offset:96
	global_load_dwordx4 v[64:67], v242, s[20:21] offset:128
	global_load_dwordx4 v[68:71], v242, s[20:21] offset:160
	global_load_dwordx4 v[72:75], v242, s[20:21] offset:192
	global_load_dwordx4 v[76:79], v242, s[20:21] offset:224
	global_load_dwordx4 v[96:99], v242, s[20:21] offset:256
	global_load_dwordx4 v[100:103], v242, s[20:21] offset:288
	global_load_dwordx4 v[104:107], v242, s[20:21] offset:320
	global_load_dwordx4 v[108:111], v242, s[20:21] offset:352
	global_load_dwordx4 v[112:115], v242, s[20:21] offset:384
	global_load_dwordx4 v[116:119], v242, s[20:21] offset:416
	global_load_dwordx4 v[120:123], v242, s[20:21] offset:448
	global_load_dwordx4 v[124:127], v242, s[20:21] offset:480
	global_load_dword v154, v243, s[26:27]
	v_add_u32_e32 v162, s55, v250
	v_and_b32_e32 v162, 0xfff, v162
	v_lshrrev_b32_e32 v163, 6, v162
	v_lshl_add_u32 v163, v163, 5, v251
	global_load_dwordx4 v[130:133], v163, s[30:31]
	global_load_dwordx4 v[134:137], v163, s[30:31] offset:2048
	v_and_b32_e32 v162, 63, v162
	v_lshl_add_u32 v162, v162, 5, v251
	global_load_dwordx4 v[138:141], v162, s[30:31]
	global_load_dwordx4 v[158:161], v162, s[30:31] offset:2048
	s_waitcnt vmcnt(0)

.Lq_drain0:
	s_nop 7
	s_nop 7
	v_mul_f32_e32 v0, v0, v155
	v_mul_f32_e32 v1, v1, v155
	v_mul_f32_e32 v2, v2, v155
	v_mul_f32_e32 v3, v3, v155
	v_mul_f32_e32 v4, v4, v155
	v_mul_f32_e32 v5, v5, v155
	v_mul_f32_e32 v6, v6, v155
	v_mul_f32_e32 v7, v7, v155
	v_mul_f32_e32 v8, v8, v155
	v_mul_f32_e32 v9, v9, v155
	v_mul_f32_e32 v10, v10, v155
	v_mul_f32_e32 v11, v11, v155
	v_mul_f32_e32 v12, v12, v155
	v_mul_f32_e32 v13, v13, v155
	v_mul_f32_e32 v14, v14, v155
	v_mul_f32_e32 v15, v15, v155
	s_cmp_eq_u32 s16, 2
	s_cbranch_scc0 .Lq_nrd0
	v_mul_f32_e32 v162, v4, v134
	v_mul_f32_e32 v163, v0, v134
	v_fma_f32 v0, v0, v130, -v162
	v_fma_f32 v4, v4, v130, v163
	v_mul_f32_e32 v162, v5, v135
	v_mul_f32_e32 v163, v1, v135
	v_fma_f32 v1, v1, v131, -v162
	v_fma_f32 v5, v5, v131, v163
	v_mul_f32_e32 v162, v6, v136
	v_mul_f32_e32 v163, v2, v136
	v_fma_f32 v2, v2, v132, -v162
	v_fma_f32 v6, v6, v132, v163
	v_mul_f32_e32 v162, v7, v137
	v_mul_f32_e32 v163, v3, v137
	v_fma_f32 v3, v3, v133, -v162
	v_fma_f32 v7, v7, v133, v163
	v_mul_f32_e32 v162, v12, v158
	v_mul_f32_e32 v163, v8, v158
	v_fma_f32 v8, v8, v138, -v162
	v_fma_f32 v12, v12, v138, v163
	v_mul_f32_e32 v162, v13, v159
	v_mul_f32_e32 v163, v9, v159
	v_fma_f32 v9, v9, v139, -v162
	v_fma_f32 v13, v13, v139, v163
	v_mul_f32_e32 v162, v14, v160
	v_mul_f32_e32 v163, v10, v160
	v_fma_f32 v10, v10, v140, -v162
	v_fma_f32 v14, v14, v140, v163
	v_mul_f32_e32 v162, v15, v161
	v_mul_f32_e32 v163, v11, v161
	v_fma_f32 v11, v11, v141, -v162
	v_fma_f32 v15, v15, v141, v163
.Lq_nrd0:
	v_mul_f32_e32 v0, s23, v0
	v_mul_f32_e32 v1, s23, v1
	v_mul_f32_e32 v2, s23, v2
	v_mul_f32_e32 v3, s23, v3
	v_mul_f32_e32 v4, s23, v4
	v_mul_f32_e32 v5, s23, v5
	v_mul_f32_e32 v6, s23, v6
	v_mul_f32_e32 v7, s23, v7
	v_mul_f32_e32 v8, s23, v8
	v_mul_f32_e32 v9, s23, v9
	v_mul_f32_e32 v10, s23, v10
	v_mul_f32_e32 v11, s23, v11
	v_mul_f32_e32 v12, s23, v12
	v_mul_f32_e32 v13, s23, v13
	v_mul_f32_e32 v14, s23, v14
	v_mul_f32_e32 v15, s23, v15
	v_cvt_pk_bf16_f32 v144, v0, v1
	v_cvt_pk_bf16_f32 v145, v2, v3
	v_cvt_pk_bf16_f32 v148, v4, v5
	v_cvt_pk_bf16_f32 v149, v6, v7
	v_cvt_pk_bf16_f32 v146, v8, v9
	v_cvt_pk_bf16_f32 v147, v10, v11
	v_cvt_pk_bf16_f32 v150, v12, v13
	v_cvt_pk_bf16_f32 v151, v14, v15
	s_nop 1
	v_permlane32_swap_b32_e32 v144, v146
	v_permlane32_swap_b32_e32 v145, v147
	v_permlane32_swap_b32_e32 v148, v150
	v_permlane32_swap_b32_e32 v149, v151
	global_store_dwordx4 v244, v[144:147], s[12:13]
	global_store_dwordx4 v244, v[148:151], s[12:13] offset:16
	s_branch .Lq_done
.Lq_drain1:
	s_nop 7
	s_nop 7
	v_mul_f32_e32 v16, v16, v155
	v_mul_f32_e32 v17, v17, v155
	v_mul_f32_e32 v18, v18, v155
	v_mul_f32_e32 v19, v19, v155
	v_mul_f32_e32 v20, v20, v155
	v_mul_f32_e32 v21, v21, v155
	v_mul_f32_e32 v22, v22, v155
	v_mul_f32_e32 v23, v23, v155
	v_mul_f32_e32 v24, v24, v155
	v_mul_f32_e32 v25, v25, v155
	v_mul_f32_e32 v26, v26, v155
	v_mul_f32_e32 v27, v27, v155
	v_mul_f32_e32 v28, v28, v155
	v_mul_f32_e32 v29, v29, v155
	v_mul_f32_e32 v30, v30, v155
	v_mul_f32_e32 v31, v31, v155
	s_cmp_eq_u32 s16, 2
	s_cbranch_scc0 .Lq_nrd1
	v_mul_f32_e32 v162, v20, v134
	v_mul_f32_e32 v163, v16, v134
	v_fma_f32 v16, v16, v130, -v162
	v_fma_f32 v20, v20, v130, v163
	v_mul_f32_e32 v162, v21, v135
	v_mul_f32_e32 v163, v17, v135
	v_fma_f32 v17, v17, v131, -v162
	v_fma_f32 v21, v21, v131, v163
	v_mul_f32_e32 v162, v22, v136
	v_mul_f32_e32 v163, v18, v136
	v_fma_f32 v18, v18, v132, -v162
	v_fma_f32 v22, v22, v132, v163
	v_mul_f32_e32 v162, v23, v137
	v_mul_f32_e32 v163, v19, v137
	v_fma_f32 v19, v19, v133, -v162
	v_fma_f32 v23, v23, v133, v163
	v_mul_f32_e32 v162, v28, v158
	v_mul_f32_e32 v163, v24, v158
	v_fma_f32 v24, v24, v138, -v162
	v_fma_f32 v28, v28, v138, v163
	v_mul_f32_e32 v162, v29, v159
	v_mul_f32_e32 v163, v25, v159
	v_fma_f32 v25, v25, v139, -v162
	v_fma_f32 v29, v29, v139, v163
	v_mul_f32_e32 v162, v30, v160
	v_mul_f32_e32 v163, v26, v160
	v_fma_f32 v26, v26, v140, -v162
	v_fma_f32 v30, v30, v140, v163
	v_mul_f32_e32 v162, v31, v161
	v_mul_f32_e32 v163, v27, v161
	v_fma_f32 v27, v27, v141, -v162
	v_fma_f32 v31, v31, v141, v163
.Lq_nrd1:
	v_mul_f32_e32 v16, s23, v16
	v_mul_f32_e32 v17, s23, v17
	v_mul_f32_e32 v18, s23, v18
	v_mul_f32_e32 v19, s23, v19
	v_mul_f32_e32 v20, s23, v20
	v_mul_f32_e32 v21, s23, v21
	v_mul_f32_e32 v22, s23, v22
	v_mul_f32_e32 v23, s23, v23
	v_mul_f32_e32 v24, s23, v24
	v_mul_f32_e32 v25, s23, v25
	v_mul_f32_e32 v26, s23, v26
	v_mul_f32_e32 v27, s23, v27
	v_mul_f32_e32 v28, s23, v28
	v_mul_f32_e32 v29, s23, v29
	v_mul_f32_e32 v30, s23, v30
	v_mul_f32_e32 v31, s23, v31
	v_cvt_pk_bf16_f32 v144, v16, v17
	v_cvt_pk_bf16_f32 v145, v18, v19
	v_cvt_pk_bf16_f32 v148, v20, v21
	v_cvt_pk_bf16_f32 v149, v22, v23
	v_cvt_pk_bf16_f32 v146, v24, v25
	v_cvt_pk_bf16_f32 v147, v26, v27
	v_cvt_pk_bf16_f32 v150, v28, v29
	v_cvt_pk_bf16_f32 v151, v30, v31
	s_nop 1
	v_permlane32_swap_b32_e32 v144, v146
	v_permlane32_swap_b32_e32 v145, v147
	v_permlane32_swap_b32_e32 v148, v150
	v_permlane32_swap_b32_e32 v149, v151
	global_store_dwordx4 v244, v[144:147], s[12:13]
	global_store_dwordx4 v244, v[148:151], s[12:13] offset:16
	s_branch .Lq_done
